# modulation GEMV: the 32 second-round items (layer 3) run in layer 0's first G1 idle tail instead of the prologue
# speedup vs baseline: 1.0180x; 1.0057x over previous
; #define LAS __attribute__((address_space(3)))
; __device__ __forceinline__ float silu_f(float g) { return g * __builtin_amdgcn_rcpf(1.f + __expf(-g)); }
; __device__ __forceinline__ void prologue_a(const Args& a, LAS unsigned char* lds, int tid, int G) {
;     ...
;     {
;         LAS float* sc = (LAS float*)lds;
;         LAS float* red = (LAS float*)(lds + 9 * 1024 * 4);
;         for (int i = tid; i < 9 * 1024; i += 512) { const int m = i >> 10, k = i & 1023; const float v = (m < 8) ? a.in[I_C][m * 1024 + k] : a.in[I_CCTX][k]; sc[i] = silu_f(v); }
;         __syncthreads();
.LBB0_55:
	s_or_b64 exec, exec, s[0:1]
	s_mov_b32 s32, s2
.Lgv_entry:
	s_movk_i32 s0, 0x2400
	v_cmp_gt_i32_e32 vcc, s0, v158
	v_ashrrev_i32_e32 v159, 31, v158
	s_barrier
	s_and_saveexec_b64 s[0:1], vcc
	s_cbranch_execz .LBB0_58
	v_lshl_add_u32 v4, v158, 2, 0
	v_lshl_add_u64 v[2:3], v[158:159], 2, s[78:79]
	s_mov_b64 s[8:9], 0
	v_mov_b32_e32 v5, v158

; __device__ __forceinline__ void prologue_a(const Args& a, LAS unsigned char* lds, int tid, int G) {
;     ...
;         float* MOD = (float*)(ws + WS_MOD);
;         const int kq = tid >> 7, jj = tid & 127;
;         for (int it = blockIdx.x; it < DEPTH * 72; it += G) {
;             const int l = it / 72, cb = it % 72, col = cb * 128 + jj;
;             const float* wp = a.in[I_WMOD] + (size_t)l * DM * 9216 + col;
;             float acc[9];
; #pragma unroll
;             for (int m = 0; m < 9; ++m) acc[m] = 0.f;
; #pragma unroll 4
;             for (int k = kq * 256; k < kq * 256 + 256; ++k) {
;     ...
;             __syncthreads();
;         }
.LBB0_58:
	s_or_b64 exec, exec, s[0:1]
	v_readlane_b32 s0, v252, 19
	v_readlane_b32 s1, v252, 20
	s_andn2_b64 vcc, exec, s[0:1]
	s_waitcnt lgkmcnt(0)
	s_barrier
	s_cbranch_vccnz .LBB0_66
	v_ashrrev_i32_e32 v6, 7, v158
	s_movk_i32 s0, 0x480
	v_and_b32_e32 v16, 0x7f, v158
	v_lshlrev_b32_e32 v7, 8, v6
	v_cmp_gt_i32_e32 vcc, s0, v158
	s_movk_i32 s0, 0x1200
	v_mov_b64_e32 v[4:5], s[84:85]
	v_lshlrev_b32_e32 v0, 2, v16
	v_mul_lo_u32 v8, v6, s0
	v_mad_i64_i32 v[4:5], s[0:1], v7, s59, v[4:5]
	v_add_u32_e32 v17, 0, v0
	s_add_i32 s0, 0, 0x9000
	v_lshl_add_u64 v[2:3], s[92:93], 0, v[0:1]
	v_lshl_add_u32 v0, v6, 10, 0
	v_lshl_add_u32 v18, v158, 2, s0
	v_add_u32_e32 v19, v17, v8
	s_mov_b32 s3, s32
	s_branch .LBB0_61
.LBB0_60:
	s_or_b64 exec, exec, s[10:11]
	s_add_i32 s3, s3, s58
	s_cmpk_gt_i32 s3, 0xff
	s_barrier
	s_cbranch_scc1 .LBB0_66

; __device__ __forceinline__ void prologue_a(const Args& a, LAS unsigned char* lds, int tid, int G) {
;     ...
;     if (blockIdx.x == 0) {
;         f32x2* rope = (f32x2*)(ws + WS_ROPE);
;         for (int i = tid; i < 64 * 16; i += 512) { const int pos = i >> 4, j = i & 15; const float inv = powf(10000.0f, -(float)j / 16.0f); const float ang = (float)pos * inv; rope[i] = (f32x2){cosf(ang), sinf(ang)}; }
.LBB0_66:
	s_cmp_lg_u32 s6, 0
	s_cbranch_scc1 .Ldef_ret
	s_movk_i32 s0, 0x400
	v_cmp_gt_i32_e32 vcc, s0, v158
	v_readlane_b32 s0, v252, 21
	v_readlane_b32 s1, v252, 22
	s_and_b64 s[0:1], s[0:1], vcc
	s_and_saveexec_b64 s[8:9], s[0:1]
	s_cbranch_execz .LBB0_77
	v_and_b32_e32 v0, 15, v158
	v_cvt_f32_ubyte0_e32 v0, v0
	v_mul_f32_e32 v0, 0xbd800000, v0
	v_cmp_eq_f32_e32 vcc, 0, v0
	s_mov_b32 s0, 0x3f2aaaab
	s_movk_i32 s3, 0x204
	v_cndmask_b32_e64 v12, v197, 1.0, vcc
	v_frexp_mant_f32_e32 v2, v12
	v_cmp_gt_f32_e64 s[0:1], s0, v2
	s_mov_b32 s10, 0x42b17218
	s_nop 0
	v_cndmask_b32_e64 v3, 1.0, 2.0, s[0:1]
	v_mul_f32_e32 v2, v2, v3
	v_add_f32_e32 v5, 1.0, v2
	v_rcp_f32_e32 v10, v5
	v_add_f32_e32 v3, -1.0, v5
	v_sub_f32_e32 v7, v2, v3
	v_add_f32_e32 v3, -1.0, v2
	v_mul_f32_e32 v11, v3, v10
	v_mul_f32_e32 v4, v5, v11
	v_fma_f32 v6, v11, v5, -v4
	v_fmac_f32_e32 v6, v11, v7
	v_add_f32_e32 v2, v4, v6
	v_sub_f32_e32 v5, v3, v2
	v_pk_add_f32 v[8:9], v[2:3], v[4:5] neg_lo:[0,1] neg_hi:[0,1]
	v_mov_b32_e32 v7, v2
	v_pk_add_f32 v[2:3], v[8:9], v[6:7] neg_lo:[0,1] neg_hi:[0,1]
	v_mov_b32_e32 v6, 0x3e91f4c4
	v_add_f32_e32 v2, v2, v3
	v_add_f32_e32 v2, v5, v2
	v_mul_f32_e32 v3, v10, v2
	v_add_f32_e32 v2, v11, v3
	v_sub_f32_e32 v4, v2, v11
	v_sub_f32_e32 v13, v3, v4
	v_mul_f32_e32 v3, v2, v2
	v_fma_f32 v5, v2, v2, -v3
	v_add_f32_e32 v4, v13, v13
	v_fmac_f32_e32 v5, v2, v4
	v_add_f32_e32 v4, v3, v5
	v_fmamk_f32 v6, v4, 0x3e76c4e1, v6
	v_fmaak_f32 v6, v4, v6, 0x3ecccdef
	v_sub_f32_e32 v3, v4, v3
	v_sub_f32_e32 v14, v5, v3
	v_mul_f32_e32 v3, v4, v6
	v_fma_f32 v5, v4, v6, -v3
	v_fmac_f32_e32 v5, v14, v6
	v_add_f32_e32 v6, v3, v5
	v_add_f32_e32 v7, 0x3f2aaaaa, v6
	v_sub_f32_e32 v3, v6, v3
	v_sub_f32_e32 v3, v5, v3
	v_add_f32_e32 v5, 0xbf2aaaaa, v7
	v_add_f32_e32 v3, 0x31739010, v3
	v_sub_f32_e32 v5, v6, v5
	v_pk_mul_f32 v[8:9], v[2:3], v[4:5]
	v_pk_add_f32 v[10:11], v[2:3], v[4:5]
	v_fma_f32 v6, v4, v2, -v8
	v_fmac_f32_e32 v6, v4, v13
	v_mov_b32_e32 v9, v11
	v_fmac_f32_e32 v6, v14, v2
	v_pk_add_f32 v[4:5], v[8:9], v[6:7]
	v_ldexp_f32 v14, v13, 1
	v_sub_f32_e32 v3, v4, v8
	v_sub_f32_e32 v3, v6, v3
	v_sub_f32_e32 v6, v7, v5
	v_add_f32_e32 v10, v11, v6
	v_pk_mul_f32 v[6:7], v[4:5], v[4:5] op_sel:[0,1] op_sel_hi:[1,0]
	v_cvt_f64_f32_e32 v[8:9], v12
	v_frexp_exp_i32_f64_e32 v7, v[8:9]
	v_subbrev_co_u32_e64 v7, s[0:1], 0, v7, s[0:1]
	v_cvt_f32_i32_e32 v7, v7
	v_fma_f32 v8, v4, v5, -v6
	v_fmac_f32_e32 v8, v4, v10
	s_mov_b32 s0, 0x3f317218
	v_mul_f32_e32 v4, 0x3f317218, v7
	v_fmac_f32_e32 v8, v3, v5
	v_fma_f32 v10, v7, s0, -v4
	v_fmac_f32_e32 v10, 0xb102e308, v7
	v_ldexp_f32 v11, v2, 1
	v_add_f32_e32 v5, v6, v8
	v_pk_add_f32 v[2:3], v[4:5], v[10:11]
	v_mov_b32_e32 v12, v5
	v_mov_b32_e32 v13, v3
	v_mov_b32_e32 v7, v11
	v_pk_add_f32 v[6:7], v[12:13], v[6:7] neg_lo:[0,1] neg_hi:[0,1]
	v_mov_b32_e32 v9, v5
	v_pk_add_f32 v[6:7], v[8:9], v[6:7] neg_lo:[0,1] neg_hi:[0,1]
	v_mov_b32_e32 v11, v2
	v_add_f32_e32 v5, v14, v6
	v_add_f32_e32 v5, v5, v7
	v_pk_add_f32 v[6:7], v[2:3], v[4:5] neg_lo:[0,1] neg_hi:[0,1]
	v_pk_add_f32 v[8:9], v[2:3], v[4:5]
	v_mov_b32_e32 v4, v5
	v_mov_b32_e32 v7, v9
	v_pk_add_f32 v[12:13], v[10:11], v[6:7] neg_lo:[0,1] neg_hi:[0,1]
	v_pk_add_f32 v[6:7], v[10:11], v[6:7]
	v_mov_b32_e32 v5, v2
	v_pk_add_f32 v[10:11], v[6:7], v[2:3] op_sel:[1,0] op_sel_hi:[0,1] neg_lo:[0,1] neg_hi:[0,1]
	v_pk_add_f32 v[14:15], v[8:9], v[10:11] op_sel_hi:[1,0] neg_lo:[0,1] neg_hi:[0,1]
	v_mov_b32_e32 v8, v9
	v_mov_b32_e32 v9, v7
	v_pk_mov_b32 v[10:11], v[2:3], v[10:11] op_sel:[1,0]
	v_mov_b32_e32 v14, v12
	v_pk_add_f32 v[8:9], v[8:9], v[10:11] neg_lo:[0,1] neg_hi:[0,1]
	v_mov_b32_e32 v13, v7
	v_pk_add_f32 v[2:3], v[4:5], v[8:9] neg_lo:[0,1] neg_hi:[0,1]
	s_nop 0
	v_pk_add_f32 v[4:5], v[14:15], v[2:3]
	s_nop 0
	v_pk_add_f32 v[8:9], v[4:5], v[4:5] op_sel:[0,1] op_sel_hi:[1,0]
	s_nop 0
	v_pk_add_f32 v[6:7], v[6:7], v[8:9] op_sel:[1,0] op_sel_hi:[0,1]
	v_mov_b32_e32 v5, v6
	v_pk_add_f32 v[10:11], v[4:5], v[12:13] neg_lo:[0,1] neg_hi:[0,1]
	v_mov_b32_e32 v3, v8
	v_sub_f32_e32 v4, v4, v10
	v_pk_add_f32 v[2:3], v[2:3], v[10:11] neg_lo:[0,1] neg_hi:[0,1]
	v_sub_f32_e32 v4, v12, v4
	v_add_f32_e32 v2, v2, v4
	v_add_f32_e32 v2, v2, v3
	v_add_f32_e32 v3, v6, v2
	v_sub_f32_e32 v4, v3, v6
	v_sub_f32_e32 v2, v2, v4
	v_mul_f32_e32 v4, v0, v3
	v_fma_f32 v3, v0, v3, -v4
	v_fmac_f32_e32 v3, v0, v2
	v_add_f32_e32 v2, v4, v3
	v_cmp_class_f32_e64 s[0:1], v4, s3
	v_sub_f32_e32 v5, v2, v4
	v_sub_f32_e32 v3, v3, v5
	v_cndmask_b32_e64 v2, v2, v4, s[0:1]
	v_cmp_eq_f32_e64 s[0:1], s10, v2
	s_nop 1
	v_cndmask_b32_e64 v4, 0, v198, s[0:1]
	v_sub_f32_e32 v5, v2, v4
	v_mul_f32_e32 v6, 0x3fb8aa3b, v5
	s_mov_b32 s0, 0x3fb8aa3b
	v_fma_f32 v7, v5, s0, -v6
	v_rndne_f32_e32 v8, v6
	v_fmac_f32_e32 v7, 0x32a5705f, v5
	v_sub_f32_e32 v6, v6, v8
	v_add_f32_e32 v6, v6, v7
	v_exp_f32_e32 v6, v6
	v_cvt_i32_f32_e32 v7, v8
	s_mov_b32 s0, 0x7f800000
	v_cmp_neq_f32_e64 s[0:1], |v2|, s0
	s_nop 1
	v_cndmask_b32_e64 v2, 0, v3, s[0:1]
	s_mov_b32 s0, 0xc2ce8ed0
	v_ldexp_f32 v3, v6, v7
	v_cmp_ngt_f32_e64 s[0:1], s0, v5
	v_add_f32_e32 v2, v4, v2
	s_nop 0
	v_cndmask_b32_e64 v3, 0, v3, s[0:1]
	v_cmp_nlt_f32_e64 s[0:1], s10, v5
	s_mov_b64 s[10:11], 0
	v_mov_b32_e32 v5, v158
	v_cndmask_b32_e64 v3, v204, v3, s[0:1]
	v_fma_f32 v2, v3, v2, v3
	v_cmp_class_f32_e64 s[0:1], v3, s3
	s_nop 1
	v_cndmask_b32_e64 v2, v2, v3, s[0:1]
	v_cmp_neq_f32_e64 s[0:1], v0, |v0|
	s_nop 1
	v_cndmask_b32_e64 v3, v204, 0, s[0:1]
	v_cndmask_b32_e64 v3, v3, 1.0, vcc
	v_cmp_class_f32_e64 s[0:1], v0, s3
	s_nop 1
	v_cndmask_b32_e64 v4, |v2|, v3, s[0:1]
	v_readlane_b32 s0, v254, 29
	v_readlane_b32 s1, v254, 30
	s_nop 1
	v_lshl_add_u64 v[2:3], v[158:159], 3, s[0:1]
	s_branch .LBB0_69

; __device__ __forceinline__ void prologue_a(const Args& a, LAS unsigned char* lds, int tid, int G) {
;     ...
;         for (int it = blockIdx.x; it < DEPTH * 72; it += G) {
; __global__ void __launch_bounds__(512, 2) mega_fwd(Args a) {
;     ...
;             const int q = p - 2, l = q / 10, st = q % 10; const bool last = (l == DEPTH - 1);
;             const int Mfull = TT, Mlate = last ? T_LAT : TT;
;             if (st == 0 || st == 7) {
;                 const int sub = (st == 7), M = sub ? Mlate : Mfull;
;                 pg8::Gemm g{(const bf16_t*)(ws + WS_Y), (const bf16_t*)(ws + WS_WGU) + (size_t)(l * 2 + sub) * NGU * DM, M, NGU, DM};
;                 pg8::StaticOrder S; S.init(M, NGU, G, (int)blockIdx.x); S.nkt = DM / pg8::BK;
;                 pg8::EpiSwiGLU E{(bf16_t*)(ws + WS_R1)};
;                 pg8::gemm_phase<pg8::EpiSwiGLU, pg8::StaticOrder, true, true>(lds, g, S, E, tid);
.LBB0_598:
	s_waitcnt vmcnt(0)
	v_readlane_b32 s22, v254, 35
	v_readlane_b32 s24, v254, 37
	v_readlane_b32 s0, v254, 39
	v_readlane_b32 s60, v254, 41
	v_readlane_b32 s28, v254, 43
	v_readlane_b32 s20, v254, 45
	s_barrier
	v_readlane_b32 s23, v254, 36
	v_readlane_b32 s25, v254, 38
	v_readlane_b32 s1, v254, 40
	s_mov_b32 s26, s0
	v_readlane_b32 s61, v254, 42
	v_readlane_b32 s29, v254, 44
	v_readlane_b32 s21, v254, 46
	s_add_i32 s8, s6, -2
	s_mul_hi_u32 s9, s8, 0xcccccccd
	s_lshr_b32 s9, s9, 3
	s_mul_i32 s10, s9, 10
	s_sub_i32 s10, s8, s10
	s_cmp_lt_u32 s2, 48
	s_cbranch_scc1 .Ldef_skip
	s_cmp_eq_u32 s10, 7
	s_cbranch_scc1 .Ldef_st7
	s_movk_i32 s101, 0x680
	s_cmp_lg_u32 s9, 0
	s_cbranch_scc1 .Ldef_nogv
	s_cmpk_lt_u32 s2, 0xe0
	s_cbranch_scc1 .Ldef_gvconv
	s_add_i32 s32, s2, 32
	s_branch .Lgv_entry
.Ldef_gvconv:
	s_movk_i32 s101, 0x580
.Ldef_nogv:
	s_mul_i32 s9, s9, 0x2800
	s_add_i32 s32, s9, 0x2800
	s_add_i32 s9, s9, 0x1080
	s_branch .Ldef_go
.Ldef_st7:
	s_movk_i32 s101, 0x680
	s_cmp_gt_u32 s9, 2
	s_cbranch_scc1 .Ldef_skip
	s_add_i32 s9, s9, 1
	s_mul_i32 s9, s9, 0x2800
	s_add_i32 s32, s9, 0x1080
.Ldef_go:
	s_add_i32 s100, s9, s99
	s_add_i32 s100, s100, 0xfffffe80
	s_branch .Ldef_entry
